# v22 plus lazy online-softmax rescale (only when block max exceeds reference by 2^8)
# speedup vs baseline: 1.0004x; 1.0004x over previous
; #define LAS __attribute__((address_space(3)))
; __device__ __forceinline__ float shflx(float v, int mask, int lane) { return __builtin_bit_cast(float, __builtin_amdgcn_ds_bpermute(((lane ^ mask) & 63) << 2, __builtin_bit_cast(int, v))); }
; template <int MODE  > ...
;     ...
;             for (int kk = 0; kk < 4; ++kk) {
;                 const bf16x8 k0 = *(const LAS bf16x8*)(kb + col * KPITCH + kk * 16 + h * 8);
;                 const bf16x8 k1 = *(const LAS bf16x8*)(kb + (32 + col) * KPITCH + kk * 16 + h * 8);
;                 s0 = __builtin_amdgcn_mfma_f32_32x32x16_bf16(k0, qf[kk], s0, 0, 0, 0);
;                 s1 = __builtin_amdgcn_mfma_f32_32x32x16_bf16(k1, qf[kk], s1, 0, 0, 0);
;             }
;             if (MODE != 3) {
;                 float mx = fmaxf(s0[0], s1[0]);
; #pragma unroll
;                 for (int i = 1; i < 16; ++i) mx = fmaxf(mx, fmaxf(s0[i], s1[i]));
;                 mx = fmaxf(mx, shflx(mx, 32, lane));
;                 float alpha = 1.f;
;                 if (__builtin_amdgcn_ballot_w64(fresh || mx > 0.f) != 0ull) {
;                     const float moldr = fresh ? -1e29f : 0.f, mnewr = fmaxf(moldr, mx);
;                     alpha = __builtin_amdgcn_exp2f(moldr - mnewr);
;                     st.m = mest + mnewr;
; #pragma unroll
;                     for (int i = 0; i < 16; ++i) { s0[i] = __builtin_amdgcn_exp2f(s0[i] - mnewr); s1[i] = __builtin_amdgcn_exp2f(s1[i] - mnewr); }
;                     st.o0 *= alpha; st.o1 *= alpha;
.Lm0_qk:
	s_waitcnt lgkmcnt(7)
	v_mfma_f32_32x32x16_bf16 v[64:79], v[80:83], v[144:147], v[64:79]
	s_waitcnt lgkmcnt(6)
	v_mfma_f32_32x32x16_bf16 v[48:63], v[84:87], v[144:147], v[48:63]
	s_waitcnt lgkmcnt(5)
	v_mfma_f32_32x32x16_bf16 v[64:79], v[88:91], v[148:151], v[64:79]
	s_waitcnt lgkmcnt(4)
	v_mfma_f32_32x32x16_bf16 v[48:63], v[92:95], v[148:151], v[48:63]
	s_waitcnt lgkmcnt(3)
	v_mfma_f32_32x32x16_bf16 v[64:79], v[96:99], v[152:155], v[64:79]
	s_waitcnt lgkmcnt(2)
	v_mfma_f32_32x32x16_bf16 v[48:63], v[100:103], v[152:155], v[48:63]
	s_waitcnt lgkmcnt(1)
	v_mfma_f32_32x32x16_bf16 v[64:79], v[104:107], v[156:159], v[64:79]
	s_waitcnt lgkmcnt(0)
	v_mfma_f32_32x32x16_bf16 v[48:63], v[108:111], v[156:159], v[48:63]
	ds_read_b64_tr_b16 v[80:81], v225 offset:18432
	ds_read_b64_tr_b16 v[82:83], v225 offset:19968
	ds_read_b64_tr_b16 v[84:85], v225 offset:18496
	ds_read_b64_tr_b16 v[86:87], v225 offset:20032
	ds_read_b64_tr_b16 v[88:89], v225 offset:21504
	ds_read_b64_tr_b16 v[90:91], v225 offset:23040
	ds_read_b64_tr_b16 v[92:93], v225 offset:21568
	ds_read_b64_tr_b16 v[94:95], v225 offset:23104
	s_nop 3
	v_max3_f32 v234, v64, v65, v66
	v_max3_f32 v234, v234, v67, v68
	v_max3_f32 v234, v234, v69, v70
	v_max3_f32 v234, v234, v71, v72
	v_max3_f32 v234, v234, v73, v74
	v_max3_f32 v234, v234, v75, v76
	v_max3_f32 v234, v234, v77, v78
	v_max3_f32 v235, v48, v49, v50
	v_max3_f32 v235, v235, v51, v52
	v_max3_f32 v235, v235, v53, v54
	v_max3_f32 v235, v235, v55, v56
	v_max3_f32 v235, v235, v57, v58
	v_max3_f32 v235, v235, v59, v60
	v_max3_f32 v235, v235, v61, v62
	v_max3_f32 v234, v234, v79, v63
	v_max_f32_e32 v234, v234, v235
	v_mov_b32_e32 v235, v234
	s_waitcnt lgkmcnt(7)
	ds_read_b64_tr_b16 v[96:97], v225 offset:24576
	ds_read_b64_tr_b16 v[98:99], v225 offset:26112
	ds_read_b64_tr_b16 v[100:101], v225 offset:24640
	ds_read_b64_tr_b16 v[102:103], v225 offset:26176
	ds_read_b64_tr_b16 v[104:105], v225 offset:27648
	ds_read_b64_tr_b16 v[106:107], v225 offset:29184
	ds_read_b64_tr_b16 v[108:109], v225 offset:27712
	ds_read_b64_tr_b16 v[110:111], v225 offset:29248
	v_permlane32_swap_b32_e32 v235, v234
	v_max_f32_e32 v234, v234, v235
	v_cmp_lt_f32_e32 vcc, 0x41000000, v234
	s_or_b64 vcc, s[14:15], vcc
	s_cbranch_vccz .Lm0_norescale
	v_cndmask_b32_e64 v235, 0, v242, s[14:15]
	v_max_f32_e32 v234, v235, v234
	v_sub_f32_e32 v235, v235, v234
	v_exp_f32_e32 v6, v235
	v_add_f32_e32 v219, v1, v234
	v_sub_f32_e32 v128, v64, v234
	v_exp_f32_e32 v128, v128
	v_sub_f32_e32 v112, v48, v234
	v_exp_f32_e32 v112, v112
	v_sub_f32_e32 v129, v65, v234
	v_exp_f32_e32 v129, v129
	v_sub_f32_e32 v113, v49, v234
	v_exp_f32_e32 v113, v113
	v_sub_f32_e32 v130, v66, v234
	v_exp_f32_e32 v130, v130
	v_sub_f32_e32 v114, v50, v234
	v_exp_f32_e32 v114, v114
	v_sub_f32_e32 v131, v67, v234
	v_exp_f32_e32 v131, v131
	v_sub_f32_e32 v115, v51, v234
	v_exp_f32_e32 v115, v115
	v_sub_f32_e32 v132, v68, v234
	v_exp_f32_e32 v132, v132
	v_sub_f32_e32 v116, v52, v234
	v_exp_f32_e32 v116, v116
	v_sub_f32_e32 v133, v69, v234
	v_exp_f32_e32 v133, v133
	v_sub_f32_e32 v117, v53, v234
	v_exp_f32_e32 v117, v117
	v_sub_f32_e32 v134, v70, v234
	v_exp_f32_e32 v134, v134
	v_sub_f32_e32 v118, v54, v234
	v_exp_f32_e32 v118, v118
	v_sub_f32_e32 v135, v71, v234
	v_exp_f32_e32 v135, v135
	v_sub_f32_e32 v119, v55, v234
	v_exp_f32_e32 v119, v119
	v_sub_f32_e32 v136, v72, v234
	v_exp_f32_e32 v136, v136
	v_sub_f32_e32 v120, v56, v234
	v_exp_f32_e32 v120, v120
	v_sub_f32_e32 v137, v73, v234
	v_exp_f32_e32 v137, v137
	v_sub_f32_e32 v121, v57, v234
	v_exp_f32_e32 v121, v121
	v_sub_f32_e32 v138, v74, v234
	v_exp_f32_e32 v138, v138
	v_sub_f32_e32 v122, v58, v234
	v_exp_f32_e32 v122, v122
	v_sub_f32_e32 v139, v75, v234
	v_exp_f32_e32 v139, v139
	v_sub_f32_e32 v123, v59, v234
	v_exp_f32_e32 v123, v123
	v_sub_f32_e32 v140, v76, v234
	v_exp_f32_e32 v140, v140
	v_sub_f32_e32 v124, v60, v234
	v_exp_f32_e32 v124, v124
	v_sub_f32_e32 v141, v77, v234
	v_exp_f32_e32 v141, v141
	v_sub_f32_e32 v125, v61, v234
	v_exp_f32_e32 v125, v125
	v_sub_f32_e32 v142, v78, v234
	v_exp_f32_e32 v142, v142
	v_sub_f32_e32 v126, v62, v234
	v_exp_f32_e32 v126, v126
	v_sub_f32_e32 v143, v79, v234
	v_exp_f32_e32 v143, v143
	v_sub_f32_e32 v127, v63, v234
	v_exp_f32_e32 v127, v127
	v_pk_mul_f32 v[16:17], v[16:17], v[6:7] op_sel_hi:[1,0]
	v_pk_mul_f32 v[18:19], v[18:19], v[6:7] op_sel_hi:[1,0]
	v_pk_mul_f32 v[20:21], v[20:21], v[6:7] op_sel_hi:[1,0]
	v_pk_mul_f32 v[22:23], v[22:23], v[6:7] op_sel_hi:[1,0]
	v_pk_mul_f32 v[24:25], v[24:25], v[6:7] op_sel_hi:[1,0]
	v_pk_mul_f32 v[26:27], v[26:27], v[6:7] op_sel_hi:[1,0]
	v_pk_mul_f32 v[28:29], v[28:29], v[6:7] op_sel_hi:[1,0]
	v_pk_mul_f32 v[30:31], v[30:31], v[6:7] op_sel_hi:[1,0]
	v_pk_mul_f32 v[32:33], v[32:33], v[6:7] op_sel_hi:[1,0]
	v_pk_mul_f32 v[34:35], v[34:35], v[6:7] op_sel_hi:[1,0]
	v_pk_mul_f32 v[36:37], v[36:37], v[6:7] op_sel_hi:[1,0]
	v_pk_mul_f32 v[38:39], v[38:39], v[6:7] op_sel_hi:[1,0]
	v_pk_mul_f32 v[40:41], v[40:41], v[6:7] op_sel_hi:[1,0]
	v_pk_mul_f32 v[42:43], v[42:43], v[6:7] op_sel_hi:[1,0]
	v_pk_mul_f32 v[44:45], v[44:45], v[6:7] op_sel_hi:[1,0]
	v_pk_mul_f32 v[46:47], v[46:47], v[6:7] op_sel_hi:[1,0]
	s_branch .Lm0_pv
